# Fold prepare (p8, p1 per-unit): column-sum loads issued with the row-stat loads as global loads, one wait; on top of v_mov_b64 zero-init
# baseline (speedup 1.0000x reference)
; #define LAS __attribute__((address_space(3)))
; __device__ __forceinline__ float bf_lo(unsigned w) { return __uint_as_float(w << 16); }
;     __device__ __forceinline__ void operator()(const f32x4 (&acc)[2][2][4][2], const pg8::Unit& u, int wr, int wc, int fr, int fq, LAS unsigned char* lds, int par) const {
;         const bool fold = F.stats != nullptr;
;         const LAS float* rsb = (const LAS float*)(lds + RS_OFF) + par * 512; const LAS float* cvb = (const LAS float*)(lds + CV_OFF) + (par * 2 + wr) * 512;
;         const int row0 = u.pm * 256 + wr * 64 + fr, c0 = u.pn * 256 + wc * 64 + 16 * fq;
; #pragma unroll
;         for (int ai = 0; ai < 2; ++ai)
; #pragma unroll
;             for (int m = 0; m < 4; ++m) {
;                 const int row = row0 + ai * 128 + m * 16, lrow = ai * 128 + wr * 64 + m * 16 + fr;
;                 float mu = 0.f, rstd = 1.f; if (fold) { mu = rsb[2 * lrow]; rstd = rsb[2 * lrow + 1]; }
; #pragma unroll
;                 for (int bj = 0; bj < 2; ++bj) {
;                     const size_t off = (size_t)row * ld + c0 + bj * 8;
;                     f32x4 v0 = acc[ai][bj][m][0], v1 = acc[ai][bj][m][1];
;                     if (fold) fold_apply(v0, v1, mu, rstd, cvb, wc * 64 + 16 * fq + bj * 8);
;                     if (MODE == 0) { v0 *= scale; v1 *= scale; }
;                     if (MODE == 1) {
; #pragma unroll
;                         for (int j = 0; j < 4; ++j) { const float a = fmaxf(v0[j], 0.f), b = fmaxf(v1[j], 0.f); v0[j] = a * a; v1[j] = b * b; }
;                     }
;                     if (MODE == 2 || MODE == 3) {
;                         const u32x4 gw = *(const u32x4*)(gate + off);
;                         v0[0] *= bf_lo(gw.x); v0[1] *= bf_hi(gw.x); v0[2] *= bf_lo(gw.y); v0[3] *= bf_hi(gw.y);
;                         v1[0] *= bf_lo(gw.z); v1[1] *= bf_hi(gw.z); v1[2] *= bf_lo(gw.w); v1[3] *= bf_hi(gw.w);
;                     }
;                     if (MODE == 3) {
;                         const u32x4 pw = *(const u32x4*)(o + off);
;                         v0[0] += bf_lo(pw.x); v0[1] += bf_hi(pw.x); v0[2] += bf_lo(pw.y); v0[3] += bf_hi(pw.y);
;                         v1[0] += bf_lo(pw.z); v1[1] += bf_hi(pw.z); v1[2] += bf_lo(pw.w); v1[3] += bf_hi(pw.w);
;                     }
;                     *(u32x4*)(o + off) = pack8(v0, v1);
.LBB0_176:
	s_and_b32 s15, s41, 1
	v_lshl_add_u32 v156, s15, 12, v153
	v_lshl_add_u32 v157, s15, 11, v152
	v_readlane_b32 s26, v251, 43
	v_readlane_b32 s27, v251, 44
	ds_read_b128 v[212:215], v156
	ds_read_b128 v[216:219], v156 offset:16
	ds_read_b128 v[220:223], v156 offset:32
	ds_read_b128 v[224:227], v156 offset:48
	ds_read_b128 v[228:231], v156 offset:64
	ds_read_b128 v[232:235], v156 offset:80
	ds_read_b128 v[236:239], v156 offset:96
	ds_read_b128 v[240:243], v156 offset:112
	ds_read_b64 v[172:173], v157
	ds_read_b64 v[174:175], v157 offset:128
	ds_read_b64 v[176:177], v157 offset:256
	ds_read_b64 v[178:179], v157 offset:384
	ds_read_b64 v[180:181], v157 offset:1024
	ds_read_b64 v[182:183], v157 offset:1152
	ds_read_b64 v[184:185], v157 offset:1280
	ds_read_b64 v[186:187], v157 offset:1408
	v_lshl_add_u32 v158, s24, 8, v148
	v_lshl_or_b32 v159, s40, 8, v150
	v_lshlrev_b32_e32 v201, 14, v158
	v_lshl_add_u32 v201, v159, 1, v201
	s_waitcnt lgkmcnt(0)
	v_mul_f32_e32 v200, v173, v172
	v_mov_b32_e32 v155, v201
	v_fma_f32 v188, -v200, v212, v213
	v_fma_f32 v189, -v200, v214, v215
	v_fma_f32 v190, -v200, v216, v217
	v_fma_f32 v191, -v200, v218, v219
	v_fma_f32 v192, -v200, v220, v221
	v_fma_f32 v193, -v200, v222, v223
	v_fma_f32 v194, -v200, v224, v225
	v_fma_f32 v195, -v200, v226, v227
	v_fma_f32 v126, v173, v126, v188
	v_fma_f32 v127, v173, v127, v189
	v_fma_f32 v128, v173, v128, v190
	v_fma_f32 v129, v173, v129, v191
	v_fma_f32 v122, v173, v122, v192
	v_fma_f32 v123, v173, v123, v193
	v_fma_f32 v124, v173, v124, v194
	v_fma_f32 v125, v173, v125, v195
	v_max_f32_e32 v126, 0, v126
	v_max_f32_e32 v127, 0, v127
	v_max_f32_e32 v128, 0, v128
	v_max_f32_e32 v129, 0, v129
	v_max_f32_e32 v122, 0, v122
	v_max_f32_e32 v123, 0, v123
	v_max_f32_e32 v124, 0, v124
	v_max_f32_e32 v125, 0, v125
	v_mul_f32_e32 v126, v126, v126
	v_mul_f32_e32 v127, v127, v127
	v_mul_f32_e32 v128, v128, v128
	v_mul_f32_e32 v129, v129, v129
	v_mul_f32_e32 v122, v122, v122
	v_mul_f32_e32 v123, v123, v123
	v_mul_f32_e32 v124, v124, v124
	v_mul_f32_e32 v125, v125, v125
	v_cvt_pk_bf16_f32 v196, v126, v127
	v_cvt_pk_bf16_f32 v197, v128, v129
	v_cvt_pk_bf16_f32 v198, v122, v123
	v_cvt_pk_bf16_f32 v199, v124, v125
	global_store_dwordx4 v155, v[196:199], s[26:27]
	v_fma_f32 v188, -v200, v228, v229
	v_fma_f32 v189, -v200, v230, v231
	v_fma_f32 v190, -v200, v232, v233
	v_fma_f32 v191, -v200, v234, v235
	v_fma_f32 v192, -v200, v236, v237
	v_fma_f32 v193, -v200, v238, v239
	v_fma_f32 v194, -v200, v240, v241
	v_fma_f32 v195, -v200, v242, v243
	v_fma_f32 v118, v173, v118, v188
	v_fma_f32 v119, v173, v119, v189
	v_fma_f32 v120, v173, v120, v190
	v_fma_f32 v121, v173, v121, v191
	v_fma_f32 v114, v173, v114, v192
	v_fma_f32 v115, v173, v115, v193
	v_fma_f32 v116, v173, v116, v194
	v_fma_f32 v117, v173, v117, v195
	v_max_f32_e32 v118, 0, v118
	v_max_f32_e32 v119, 0, v119
	v_max_f32_e32 v120, 0, v120
	v_max_f32_e32 v121, 0, v121
	v_max_f32_e32 v114, 0, v114
	v_max_f32_e32 v115, 0, v115
	v_max_f32_e32 v116, 0, v116
	v_max_f32_e32 v117, 0, v117
	v_mul_f32_e32 v118, v118, v118
	v_mul_f32_e32 v119, v119, v119
	v_mul_f32_e32 v120, v120, v120
	v_mul_f32_e32 v121, v121, v121
	v_mul_f32_e32 v114, v114, v114
	v_mul_f32_e32 v115, v115, v115
	v_mul_f32_e32 v116, v116, v116
	v_mul_f32_e32 v117, v117, v117
	v_cvt_pk_bf16_f32 v196, v118, v119
	v_cvt_pk_bf16_f32 v197, v120, v121
	v_cvt_pk_bf16_f32 v198, v114, v115
	v_cvt_pk_bf16_f32 v199, v116, v117
	global_store_dwordx4 v155, v[196:199], s[26:27] offset:16
	v_mul_f32_e32 v200, v175, v174
	v_add_u32_e32 v155, 0x40000, v201
	v_fma_f32 v188, -v200, v212, v213
	v_fma_f32 v189, -v200, v214, v215
	v_fma_f32 v190, -v200, v216, v217
	v_fma_f32 v191, -v200, v218, v219
	v_fma_f32 v192, -v200, v220, v221
	v_fma_f32 v193, -v200, v222, v223
	v_fma_f32 v194, -v200, v224, v225
	v_fma_f32 v195, -v200, v226, v227
	v_fma_f32 v110, v175, v110, v188
	v_fma_f32 v111, v175, v111, v189
	v_fma_f32 v112, v175, v112, v190
	v_fma_f32 v113, v175, v113, v191
	v_fma_f32 v106, v175, v106, v192
	v_fma_f32 v107, v175, v107, v193
	v_fma_f32 v108, v175, v108, v194
	v_fma_f32 v109, v175, v109, v195
	v_max_f32_e32 v110, 0, v110
	v_max_f32_e32 v111, 0, v111
	v_max_f32_e32 v112, 0, v112
	v_max_f32_e32 v113, 0, v113
	v_max_f32_e32 v106, 0, v106
	v_max_f32_e32 v107, 0, v107
	v_max_f32_e32 v108, 0, v108
	v_max_f32_e32 v109, 0, v109
	v_mul_f32_e32 v110, v110, v110
	v_mul_f32_e32 v111, v111, v111
	v_mul_f32_e32 v112, v112, v112
	v_mul_f32_e32 v113, v113, v113
	v_mul_f32_e32 v106, v106, v106
	v_mul_f32_e32 v107, v107, v107
	v_mul_f32_e32 v108, v108, v108
	v_mul_f32_e32 v109, v109, v109
	v_cvt_pk_bf16_f32 v196, v110, v111
	v_cvt_pk_bf16_f32 v197, v112, v113
	v_cvt_pk_bf16_f32 v198, v106, v107
	v_cvt_pk_bf16_f32 v199, v108, v109
	global_store_dwordx4 v155, v[196:199], s[26:27]
	v_fma_f32 v188, -v200, v228, v229
	v_fma_f32 v189, -v200, v230, v231
	v_fma_f32 v190, -v200, v232, v233
	v_fma_f32 v191, -v200, v234, v235
	v_fma_f32 v192, -v200, v236, v237
	v_fma_f32 v193, -v200, v238, v239
	v_fma_f32 v194, -v200, v240, v241
	v_fma_f32 v195, -v200, v242, v243
	v_fma_f32 v102, v175, v102, v188
	v_fma_f32 v103, v175, v103, v189
	v_fma_f32 v104, v175, v104, v190
	v_fma_f32 v105, v175, v105, v191
	v_fma_f32 v98, v175, v98, v192
	v_fma_f32 v99, v175, v99, v193
	v_fma_f32 v100, v175, v100, v194
	v_fma_f32 v101, v175, v101, v195
	v_max_f32_e32 v102, 0, v102
	v_max_f32_e32 v103, 0, v103
	v_max_f32_e32 v104, 0, v104
	v_max_f32_e32 v105, 0, v105
	v_max_f32_e32 v98, 0, v98
	v_max_f32_e32 v99, 0, v99
	v_max_f32_e32 v100, 0, v100
	v_max_f32_e32 v101, 0, v101
	v_mul_f32_e32 v102, v102, v102
	v_mul_f32_e32 v103, v103, v103
; #define LAS __attribute__((address_space(3)))
; __device__ __forceinline__ float bf_lo(unsigned w) { return __uint_as_float(w << 16); }
;     __device__ __forceinline__ void operator()(const f32x4 (&acc)[2][2][4][2], const pg8::Unit& u, int wr, int wc, int fr, int fq, LAS unsigned char* lds, int par) const {
;         const bool fold = F.stats != nullptr;
;         const LAS float* rsb = (const LAS float*)(lds + RS_OFF) + par * 512; const LAS float* cvb = (const LAS float*)(lds + CV_OFF) + (par * 2 + wr) * 512;
;         const int row0 = u.pm * 256 + wr * 64 + fr, c0 = u.pn * 256 + wc * 64 + 16 * fq;
; #pragma unroll
;         for (int ai = 0; ai < 2; ++ai)
; #pragma unroll
;             for (int m = 0; m < 4; ++m) {
;                 const int row = row0 + ai * 128 + m * 16, lrow = ai * 128 + wr * 64 + m * 16 + fr;
;                 float mu = 0.f, rstd = 1.f; if (fold) { mu = rsb[2 * lrow]; rstd = rsb[2 * lrow + 1]; }
; #pragma unroll
;                 for (int bj = 0; bj < 2; ++bj) {
;                     const size_t off = (size_t)row * ld + c0 + bj * 8;
;                     f32x4 v0 = acc[ai][bj][m][0], v1 = acc[ai][bj][m][1];
;                     if (fold) fold_apply(v0, v1, mu, rstd, cvb, wc * 64 + 16 * fq + bj * 8);
;                     if (MODE == 0) { v0 *= scale; v1 *= scale; }
;                     if (MODE == 1) {
; #pragma unroll
;                         for (int j = 0; j < 4; ++j) { const float a = fmaxf(v0[j], 0.f), b = fmaxf(v1[j], 0.f); v0[j] = a * a; v1[j] = b * b; }
;                     }
;                     if (MODE == 2 || MODE == 3) {
;                         const u32x4 gw = *(const u32x4*)(gate + off);
;                         v0[0] *= bf_lo(gw.x); v0[1] *= bf_hi(gw.x); v0[2] *= bf_lo(gw.y); v0[3] *= bf_hi(gw.y);
;                         v1[0] *= bf_lo(gw.z); v1[1] *= bf_hi(gw.z); v1[2] *= bf_lo(gw.w); v1[3] *= bf_hi(gw.w);
;                     }
;                     if (MODE == 3) {
;                         const u32x4 pw = *(const u32x4*)(o + off);
;                         v0[0] += bf_lo(pw.x); v0[1] += bf_hi(pw.x); v0[2] += bf_lo(pw.y); v0[3] += bf_hi(pw.y);
;                         v1[0] += bf_lo(pw.z); v1[1] += bf_hi(pw.z); v1[2] += bf_lo(pw.w); v1[3] += bf_hi(pw.w);
;                     }
;                     *(u32x4*)(o + off) = pack8(v0, v1);
	v_mul_f32_e32 v104, v104, v104
	v_mul_f32_e32 v105, v105, v105
	v_mul_f32_e32 v98, v98, v98
	v_mul_f32_e32 v99, v99, v99
	v_mul_f32_e32 v100, v100, v100
	v_mul_f32_e32 v101, v101, v101
	v_cvt_pk_bf16_f32 v196, v102, v103
	v_cvt_pk_bf16_f32 v197, v104, v105
	v_cvt_pk_bf16_f32 v198, v98, v99
	v_cvt_pk_bf16_f32 v199, v100, v101
	global_store_dwordx4 v155, v[196:199], s[26:27] offset:16
	v_mul_f32_e32 v200, v177, v176
	v_add_u32_e32 v155, 0x80000, v201
	v_fma_f32 v188, -v200, v212, v213
	v_fma_f32 v189, -v200, v214, v215
	v_fma_f32 v190, -v200, v216, v217
	v_fma_f32 v191, -v200, v218, v219
	v_fma_f32 v192, -v200, v220, v221
	v_fma_f32 v193, -v200, v222, v223
	v_fma_f32 v194, -v200, v224, v225
	v_fma_f32 v195, -v200, v226, v227
	v_fma_f32 v94, v177, v94, v188
	v_fma_f32 v95, v177, v95, v189
	v_fma_f32 v96, v177, v96, v190
	v_fma_f32 v97, v177, v97, v191
	v_fma_f32 v90, v177, v90, v192
	v_fma_f32 v91, v177, v91, v193
	v_fma_f32 v92, v177, v92, v194
	v_fma_f32 v93, v177, v93, v195
	v_max_f32_e32 v94, 0, v94
	v_max_f32_e32 v95, 0, v95
	v_max_f32_e32 v96, 0, v96
	v_max_f32_e32 v97, 0, v97
	v_max_f32_e32 v90, 0, v90
	v_max_f32_e32 v91, 0, v91
	v_max_f32_e32 v92, 0, v92
	v_max_f32_e32 v93, 0, v93
	v_mul_f32_e32 v94, v94, v94
	v_mul_f32_e32 v95, v95, v95
	v_mul_f32_e32 v96, v96, v96
	v_mul_f32_e32 v97, v97, v97
	v_mul_f32_e32 v90, v90, v90
	v_mul_f32_e32 v91, v91, v91
	v_mul_f32_e32 v92, v92, v92
	v_mul_f32_e32 v93, v93, v93
	v_cvt_pk_bf16_f32 v196, v94, v95
	v_cvt_pk_bf16_f32 v197, v96, v97
	v_cvt_pk_bf16_f32 v198, v90, v91
	v_cvt_pk_bf16_f32 v199, v92, v93
	global_store_dwordx4 v155, v[196:199], s[26:27]
	v_fma_f32 v188, -v200, v228, v229
	v_fma_f32 v189, -v200, v230, v231
	v_fma_f32 v190, -v200, v232, v233
	v_fma_f32 v191, -v200, v234, v235
	v_fma_f32 v192, -v200, v236, v237
	v_fma_f32 v193, -v200, v238, v239
	v_fma_f32 v194, -v200, v240, v241
	v_fma_f32 v195, -v200, v242, v243
	v_fma_f32 v86, v177, v86, v188
	v_fma_f32 v87, v177, v87, v189
	v_fma_f32 v88, v177, v88, v190
	v_fma_f32 v89, v177, v89, v191
	v_fma_f32 v82, v177, v82, v192
	v_fma_f32 v83, v177, v83, v193
	v_fma_f32 v84, v177, v84, v194
	v_fma_f32 v85, v177, v85, v195
	v_max_f32_e32 v86, 0, v86
	v_max_f32_e32 v87, 0, v87
	v_max_f32_e32 v88, 0, v88
	v_max_f32_e32 v89, 0, v89
	v_max_f32_e32 v82, 0, v82
	v_max_f32_e32 v83, 0, v83
	v_max_f32_e32 v84, 0, v84
	v_max_f32_e32 v85, 0, v85
	v_mul_f32_e32 v86, v86, v86
	v_mul_f32_e32 v87, v87, v87
	v_mul_f32_e32 v88, v88, v88
	v_mul_f32_e32 v89, v89, v89
	v_mul_f32_e32 v82, v82, v82
	v_mul_f32_e32 v83, v83, v83
	v_mul_f32_e32 v84, v84, v84
	v_mul_f32_e32 v85, v85, v85
	v_cvt_pk_bf16_f32 v196, v86, v87
	v_cvt_pk_bf16_f32 v197, v88, v89
	v_cvt_pk_bf16_f32 v198, v82, v83
	v_cvt_pk_bf16_f32 v199, v84, v85
	global_store_dwordx4 v155, v[196:199], s[26:27] offset:16
	v_mul_f32_e32 v200, v179, v178
	v_add_u32_e32 v155, 0xc0000, v201
	v_fma_f32 v188, -v200, v212, v213
	v_fma_f32 v189, -v200, v214, v215
	v_fma_f32 v190, -v200, v216, v217
	v_fma_f32 v191, -v200, v218, v219
	v_fma_f32 v192, -v200, v220, v221
	v_fma_f32 v193, -v200, v222, v223
	v_fma_f32 v194, -v200, v224, v225
	v_fma_f32 v195, -v200, v226, v227
	v_fma_f32 v78, v179, v78, v188
	v_fma_f32 v79, v179, v79, v189
	v_fma_f32 v80, v179, v80, v190
	v_fma_f32 v81, v179, v81, v191
	v_fma_f32 v74, v179, v74, v192
	v_fma_f32 v75, v179, v75, v193
	v_fma_f32 v76, v179, v76, v194
	v_fma_f32 v77, v179, v77, v195
	v_max_f32_e32 v78, 0, v78
	v_max_f32_e32 v79, 0, v79
	v_max_f32_e32 v80, 0, v80
	v_max_f32_e32 v81, 0, v81
	v_max_f32_e32 v74, 0, v74
	v_max_f32_e32 v75, 0, v75
	v_max_f32_e32 v76, 0, v76
	v_max_f32_e32 v77, 0, v77
	v_mul_f32_e32 v78, v78, v78
	v_mul_f32_e32 v79, v79, v79
	v_mul_f32_e32 v80, v80, v80
	v_mul_f32_e32 v81, v81, v81
	v_mul_f32_e32 v74, v74, v74
	v_mul_f32_e32 v75, v75, v75
	v_mul_f32_e32 v76, v76, v76
	v_mul_f32_e32 v77, v77, v77
	v_cvt_pk_bf16_f32 v196, v78, v79
	v_cvt_pk_bf16_f32 v197, v80, v81
	v_cvt_pk_bf16_f32 v198, v74, v75
	v_cvt_pk_bf16_f32 v199, v76, v77
	global_store_dwordx4 v155, v[196:199], s[26:27]
	v_fma_f32 v188, -v200, v228, v229
	v_fma_f32 v189, -v200, v230, v231
	v_fma_f32 v190, -v200, v232, v233
	v_fma_f32 v191, -v200, v234, v235
	v_fma_f32 v192, -v200, v236, v237
	v_fma_f32 v193, -v200, v238, v239
	v_fma_f32 v194, -v200, v240, v241
	v_fma_f32 v195, -v200, v242, v243
	v_fma_f32 v70, v179, v70, v188
	v_fma_f32 v71, v179, v71, v189
	v_fma_f32 v72, v179, v72, v190
	v_fma_f32 v73, v179, v73, v191
	v_fma_f32 v66, v179, v66, v192
	v_fma_f32 v67, v179, v67, v193
	v_fma_f32 v68, v179, v68, v194
	v_fma_f32 v69, v179, v69, v195
	v_max_f32_e32 v70, 0, v70
	v_max_f32_e32 v71, 0, v71
	v_max_f32_e32 v72, 0, v72
	v_max_f32_e32 v73, 0, v73
	v_max_f32_e32 v66, 0, v66
	v_max_f32_e32 v67, 0, v67
	v_max_f32_e32 v68, 0, v68
	v_max_f32_e32 v69, 0, v69
	v_mul_f32_e32 v70, v70, v70
	v_mul_f32_e32 v71, v71, v71
	v_mul_f32_e32 v72, v72, v72
	v_mul_f32_e32 v73, v73, v73
	v_mul_f32_e32 v66, v66, v66
	v_mul_f32_e32 v67, v67, v67
	v_mul_f32_e32 v68, v68, v68
	v_mul_f32_e32 v69, v69, v69
	v_cvt_pk_bf16_f32 v196, v70, v71
	v_cvt_pk_bf16_f32 v197, v72, v73
	v_cvt_pk_bf16_f32 v198, v66, v67
	v_cvt_pk_bf16_f32 v199, v68, v69
	global_store_dwordx4 v155, v[196:199], s[26:27] offset:16
	v_mul_f32_e32 v200, v181, v180
	v_add_u32_e32 v155, 0x200000, v201
	v_fma_f32 v188, -v200, v212, v213
	v_fma_f32 v189, -v200, v214, v215
	v_fma_f32 v190, -v200, v216, v217
	v_fma_f32 v191, -v200, v218, v219
	v_fma_f32 v192, -v200, v220, v221
	v_fma_f32 v193, -v200, v222, v223
	v_fma_f32 v194, -v200, v224, v225
	v_fma_f32 v195, -v200, v226, v227
	v_fma_f32 v62, v181, v62, v188
	v_fma_f32 v63, v181, v63, v189
; #define LAS __attribute__((address_space(3)))
; __device__ __forceinline__ float bf_lo(unsigned w) { return __uint_as_float(w << 16); }
;     __device__ __forceinline__ void operator()(const f32x4 (&acc)[2][2][4][2], const pg8::Unit& u, int wr, int wc, int fr, int fq, LAS unsigned char* lds, int par) const {
;         const bool fold = F.stats != nullptr;
;         const LAS float* rsb = (const LAS float*)(lds + RS_OFF) + par * 512; const LAS float* cvb = (const LAS float*)(lds + CV_OFF) + (par * 2 + wr) * 512;
;         const int row0 = u.pm * 256 + wr * 64 + fr, c0 = u.pn * 256 + wc * 64 + 16 * fq;
; #pragma unroll
;         for (int ai = 0; ai < 2; ++ai)
; #pragma unroll
;             for (int m = 0; m < 4; ++m) {
;                 const int row = row0 + ai * 128 + m * 16, lrow = ai * 128 + wr * 64 + m * 16 + fr;
;                 float mu = 0.f, rstd = 1.f; if (fold) { mu = rsb[2 * lrow]; rstd = rsb[2 * lrow + 1]; }
; #pragma unroll
;                 for (int bj = 0; bj < 2; ++bj) {
;                     const size_t off = (size_t)row * ld + c0 + bj * 8;
;                     f32x4 v0 = acc[ai][bj][m][0], v1 = acc[ai][bj][m][1];
;                     if (fold) fold_apply(v0, v1, mu, rstd, cvb, wc * 64 + 16 * fq + bj * 8);
;                     if (MODE == 0) { v0 *= scale; v1 *= scale; }
;                     if (MODE == 1) {
; #pragma unroll
;                         for (int j = 0; j < 4; ++j) { const float a = fmaxf(v0[j], 0.f), b = fmaxf(v1[j], 0.f); v0[j] = a * a; v1[j] = b * b; }
;                     }
;                     if (MODE == 2 || MODE == 3) {
;                         const u32x4 gw = *(const u32x4*)(gate + off);
;                         v0[0] *= bf_lo(gw.x); v0[1] *= bf_hi(gw.x); v0[2] *= bf_lo(gw.y); v0[3] *= bf_hi(gw.y);
;                         v1[0] *= bf_lo(gw.z); v1[1] *= bf_hi(gw.z); v1[2] *= bf_lo(gw.w); v1[3] *= bf_hi(gw.w);
;                     }
;                     if (MODE == 3) {
;                         const u32x4 pw = *(const u32x4*)(o + off);
;                         v0[0] += bf_lo(pw.x); v0[1] += bf_hi(pw.x); v0[2] += bf_lo(pw.y); v0[3] += bf_hi(pw.y);
;                         v1[0] += bf_lo(pw.z); v1[1] += bf_hi(pw.z); v1[2] += bf_lo(pw.w); v1[3] += bf_hi(pw.w);
;                     }
;                     *(u32x4*)(o + off) = pack8(v0, v1);
	v_fma_f32 v64, v181, v64, v190
	v_fma_f32 v65, v181, v65, v191
	v_fma_f32 v58, v181, v58, v192
	v_fma_f32 v59, v181, v59, v193
	v_fma_f32 v60, v181, v60, v194
	v_fma_f32 v61, v181, v61, v195
	v_max_f32_e32 v62, 0, v62
	v_max_f32_e32 v63, 0, v63
	v_max_f32_e32 v64, 0, v64
	v_max_f32_e32 v65, 0, v65
	v_max_f32_e32 v58, 0, v58
	v_max_f32_e32 v59, 0, v59
	v_max_f32_e32 v60, 0, v60
	v_max_f32_e32 v61, 0, v61
	v_mul_f32_e32 v62, v62, v62
	v_mul_f32_e32 v63, v63, v63
	v_mul_f32_e32 v64, v64, v64
	v_mul_f32_e32 v65, v65, v65
	v_mul_f32_e32 v58, v58, v58
	v_mul_f32_e32 v59, v59, v59
	v_mul_f32_e32 v60, v60, v60
	v_mul_f32_e32 v61, v61, v61
	v_cvt_pk_bf16_f32 v196, v62, v63
	v_cvt_pk_bf16_f32 v197, v64, v65
	v_cvt_pk_bf16_f32 v198, v58, v59
	v_cvt_pk_bf16_f32 v199, v60, v61
	global_store_dwordx4 v155, v[196:199], s[26:27]
	v_fma_f32 v188, -v200, v228, v229
	v_fma_f32 v189, -v200, v230, v231
	v_fma_f32 v190, -v200, v232, v233
	v_fma_f32 v191, -v200, v234, v235
	v_fma_f32 v192, -v200, v236, v237
	v_fma_f32 v193, -v200, v238, v239
	v_fma_f32 v194, -v200, v240, v241
	v_fma_f32 v195, -v200, v242, v243
	v_fma_f32 v54, v181, v54, v188
	v_fma_f32 v55, v181, v55, v189
	v_fma_f32 v56, v181, v56, v190
	v_fma_f32 v57, v181, v57, v191
	v_fma_f32 v50, v181, v50, v192
	v_fma_f32 v51, v181, v51, v193
	v_fma_f32 v52, v181, v52, v194
	v_fma_f32 v53, v181, v53, v195
	v_max_f32_e32 v54, 0, v54
	v_max_f32_e32 v55, 0, v55
	v_max_f32_e32 v56, 0, v56
	v_max_f32_e32 v57, 0, v57
	v_max_f32_e32 v50, 0, v50
	v_max_f32_e32 v51, 0, v51
	v_max_f32_e32 v52, 0, v52
	v_max_f32_e32 v53, 0, v53
	v_mul_f32_e32 v54, v54, v54
	v_mul_f32_e32 v55, v55, v55
	v_mul_f32_e32 v56, v56, v56
	v_mul_f32_e32 v57, v57, v57
	v_mul_f32_e32 v50, v50, v50
	v_mul_f32_e32 v51, v51, v51
	v_mul_f32_e32 v52, v52, v52
	v_mul_f32_e32 v53, v53, v53
	v_cvt_pk_bf16_f32 v196, v54, v55
	v_cvt_pk_bf16_f32 v197, v56, v57
	v_cvt_pk_bf16_f32 v198, v50, v51
	v_cvt_pk_bf16_f32 v199, v52, v53
	global_store_dwordx4 v155, v[196:199], s[26:27] offset:16
	v_mul_f32_e32 v200, v183, v182
	v_add_u32_e32 v155, 0x240000, v201
	v_fma_f32 v188, -v200, v212, v213
	v_fma_f32 v189, -v200, v214, v215
	v_fma_f32 v190, -v200, v216, v217
	v_fma_f32 v191, -v200, v218, v219
	v_fma_f32 v192, -v200, v220, v221
	v_fma_f32 v193, -v200, v222, v223
	v_fma_f32 v194, -v200, v224, v225
	v_fma_f32 v195, -v200, v226, v227
	v_fma_f32 v46, v183, v46, v188
	v_fma_f32 v47, v183, v47, v189
	v_fma_f32 v48, v183, v48, v190
	v_fma_f32 v49, v183, v49, v191
	v_fma_f32 v42, v183, v42, v192
	v_fma_f32 v43, v183, v43, v193
	v_fma_f32 v44, v183, v44, v194
	v_fma_f32 v45, v183, v45, v195
	v_max_f32_e32 v46, 0, v46
	v_max_f32_e32 v47, 0, v47
	v_max_f32_e32 v48, 0, v48
	v_max_f32_e32 v49, 0, v49
	v_max_f32_e32 v42, 0, v42
	v_max_f32_e32 v43, 0, v43
	v_max_f32_e32 v44, 0, v44
	v_max_f32_e32 v45, 0, v45
	v_mul_f32_e32 v46, v46, v46
	v_mul_f32_e32 v47, v47, v47
	v_mul_f32_e32 v48, v48, v48
	v_mul_f32_e32 v49, v49, v49
	v_mul_f32_e32 v42, v42, v42
	v_mul_f32_e32 v43, v43, v43
	v_mul_f32_e32 v44, v44, v44
	v_mul_f32_e32 v45, v45, v45
	v_cvt_pk_bf16_f32 v196, v46, v47
	v_cvt_pk_bf16_f32 v197, v48, v49
	v_cvt_pk_bf16_f32 v198, v42, v43
	v_cvt_pk_bf16_f32 v199, v44, v45
	global_store_dwordx4 v155, v[196:199], s[26:27]
	v_fma_f32 v188, -v200, v228, v229
	v_fma_f32 v189, -v200, v230, v231
	v_fma_f32 v190, -v200, v232, v233
	v_fma_f32 v191, -v200, v234, v235
	v_fma_f32 v192, -v200, v236, v237
	v_fma_f32 v193, -v200, v238, v239
	v_fma_f32 v194, -v200, v240, v241
	v_fma_f32 v195, -v200, v242, v243
	v_fma_f32 v38, v183, v38, v188
	v_fma_f32 v39, v183, v39, v189
	v_fma_f32 v40, v183, v40, v190
	v_fma_f32 v41, v183, v41, v191
	v_fma_f32 v34, v183, v34, v192
	v_fma_f32 v35, v183, v35, v193
	v_fma_f32 v36, v183, v36, v194
	v_fma_f32 v37, v183, v37, v195
	v_max_f32_e32 v38, 0, v38
	v_max_f32_e32 v39, 0, v39
	v_max_f32_e32 v40, 0, v40
	v_max_f32_e32 v41, 0, v41
	v_max_f32_e32 v34, 0, v34
	v_max_f32_e32 v35, 0, v35
	v_max_f32_e32 v36, 0, v36
	v_max_f32_e32 v37, 0, v37
	v_mul_f32_e32 v38, v38, v38
	v_mul_f32_e32 v39, v39, v39
	v_mul_f32_e32 v40, v40, v40
	v_mul_f32_e32 v41, v41, v41
	v_mul_f32_e32 v34, v34, v34
	v_mul_f32_e32 v35, v35, v35
	v_mul_f32_e32 v36, v36, v36
	v_mul_f32_e32 v37, v37, v37
	v_cvt_pk_bf16_f32 v196, v38, v39
	v_cvt_pk_bf16_f32 v197, v40, v41
	v_cvt_pk_bf16_f32 v198, v34, v35
	v_cvt_pk_bf16_f32 v199, v36, v37
	global_store_dwordx4 v155, v[196:199], s[26:27] offset:16
	v_mul_f32_e32 v200, v185, v184
	v_add_u32_e32 v155, 0x280000, v201
	v_fma_f32 v188, -v200, v212, v213
	v_fma_f32 v189, -v200, v214, v215
	v_fma_f32 v190, -v200, v216, v217
	v_fma_f32 v191, -v200, v218, v219
	v_fma_f32 v192, -v200, v220, v221
	v_fma_f32 v193, -v200, v222, v223
	v_fma_f32 v194, -v200, v224, v225
	v_fma_f32 v195, -v200, v226, v227
	v_fma_f32 v30, v185, v30, v188
	v_fma_f32 v31, v185, v31, v189
	v_fma_f32 v32, v185, v32, v190
	v_fma_f32 v33, v185, v33, v191
	v_fma_f32 v26, v185, v26, v192
	v_fma_f32 v27, v185, v27, v193
	v_fma_f32 v28, v185, v28, v194
	v_fma_f32 v29, v185, v29, v195
	v_max_f32_e32 v30, 0, v30
	v_max_f32_e32 v31, 0, v31
	v_max_f32_e32 v32, 0, v32
	v_max_f32_e32 v33, 0, v33
	v_max_f32_e32 v26, 0, v26
	v_max_f32_e32 v27, 0, v27
	v_max_f32_e32 v28, 0, v28
	v_max_f32_e32 v29, 0, v29
	v_mul_f32_e32 v30, v30, v30
	v_mul_f32_e32 v31, v31, v31
	v_mul_f32_e32 v32, v32, v32
	v_mul_f32_e32 v33, v33, v33
	v_mul_f32_e32 v26, v26, v26
	v_mul_f32_e32 v27, v27, v27
	v_mul_f32_e32 v28, v28, v28
	v_mul_f32_e32 v29, v29, v29
	v_cvt_pk_bf16_f32 v196, v30, v31
	v_cvt_pk_bf16_f32 v197, v32, v33
	v_cvt_pk_bf16_f32 v198, v26, v27
	v_cvt_pk_bf16_f32 v199, v28, v29
	global_store_dwordx4 v155, v[196:199], s[26:27]
;     __device__ __forceinline__ void prepare(const pg8::Unit& u, LAS unsigned char* lds, int par, int tid) const {
;         if (stats == nullptr) return;
;         const int h = tid >> 8, tt = tid & 255, rl = tt >> 1, part = tt & 1, lrow = (rl >> 6) * 128 + h * 64 + (rl & 63);
;         const float* sp = stats + ((size_t)(u.pm * 256 + lrow) * 32 + part * 16) * 2;
;         float s1 = 0.f, s2 = 0.f;
; #pragma unroll
;         for (int i = 0; i < 8; ++i) { const f32x4 v = *(const f32x4*)(sp + 4 * i); s1 += v[0] + v[2]; s2 += v[1] + v[3]; }
;         s1 += shflx(s1, 1, tid & 63); s2 += shflx(s2, 1, tid & 63);
;         const float mu = s1 * (1.f / D), var = s2 * (1.f / D) - mu * mu, rstd = __builtin_amdgcn_rsqf(var + LN_EPS);
;         if (part == 0) { LAS float* rs = (LAS float*)(lds + RS_OFF) + (par * 256 + lrow) * 2; rs[0] = mu; rs[1] = rstd; }
;         if (cs != nullptr) {
;             const int col = u.pn * 256 + tt;
;             const float c = (cs[col] + cs[N + col]) + (cs[2 * N + col] + cs[3 * N + col]);
;     __device__ __forceinline__ void operator()(const f32x4 (&acc)[2][2][4][2], const pg8::Unit& u, int wr, int wc, int fr, int fq, LAS unsigned char* lds, int par) const {
;     ...
;                     if (fold) fold_apply(v0, v1, mu, rstd, cvb, wc * 64 + 16 * fq + bj * 8);
;                     if (MODE == 0) { v0 *= scale; v1 *= scale; }
;                     if (MODE == 1) {
; #pragma unroll
;                         for (int j = 0; j < 4; ++j) { const float a = fmaxf(v0[j], 0.f), b = fmaxf(v1[j], 0.f); v0[j] = a * a; v1[j] = b * b; }
;                     }
;                     if (MODE == 2 || MODE == 3) {
;                         const u32x4 gw = *(const u32x4*)(gate + off);
;                         v0[0] *= bf_lo(gw.x); v0[1] *= bf_hi(gw.x); v0[2] *= bf_lo(gw.y); v0[3] *= bf_hi(gw.y);
;                         v1[0] *= bf_lo(gw.z); v1[1] *= bf_hi(gw.z); v1[2] *= bf_lo(gw.w); v1[3] *= bf_hi(gw.w);
;                     }
;                     if (MODE == 3) {
;                         const u32x4 pw = *(const u32x4*)(o + off);
;                         v0[0] += bf_lo(pw.x); v0[1] += bf_hi(pw.x); v0[2] += bf_lo(pw.y); v0[3] += bf_hi(pw.y);
;                         v1[0] += bf_lo(pw.z); v1[1] += bf_hi(pw.z); v1[2] += bf_lo(pw.w); v1[3] += bf_hi(pw.w);
;                     }
;                     *(u32x4*)(o + off) = pack8(v0, v1);
	v_fma_f32 v188, -v200, v228, v229
	v_fma_f32 v189, -v200, v230, v231
	v_fma_f32 v190, -v200, v232, v233
	v_fma_f32 v191, -v200, v234, v235
	v_fma_f32 v192, -v200, v236, v237
	v_fma_f32 v193, -v200, v238, v239
	v_fma_f32 v194, -v200, v240, v241
	v_fma_f32 v195, -v200, v242, v243
	v_fma_f32 v22, v185, v22, v188
	v_fma_f32 v23, v185, v23, v189
	v_fma_f32 v24, v185, v24, v190
	v_fma_f32 v25, v185, v25, v191
	v_fma_f32 v18, v185, v18, v192
	v_fma_f32 v19, v185, v19, v193
	v_fma_f32 v20, v185, v20, v194
	v_fma_f32 v21, v185, v21, v195
	v_max_f32_e32 v22, 0, v22
	v_max_f32_e32 v23, 0, v23
	v_max_f32_e32 v24, 0, v24
	v_max_f32_e32 v25, 0, v25
	v_max_f32_e32 v18, 0, v18
	v_max_f32_e32 v19, 0, v19
	v_max_f32_e32 v20, 0, v20
	v_max_f32_e32 v21, 0, v21
	v_mul_f32_e32 v22, v22, v22
	v_mul_f32_e32 v23, v23, v23
	v_mul_f32_e32 v24, v24, v24
	v_mul_f32_e32 v25, v25, v25
	v_mul_f32_e32 v18, v18, v18
	v_mul_f32_e32 v19, v19, v19
	v_mul_f32_e32 v20, v20, v20
	v_mul_f32_e32 v21, v21, v21
	v_cvt_pk_bf16_f32 v196, v22, v23
	v_cvt_pk_bf16_f32 v197, v24, v25
	v_cvt_pk_bf16_f32 v198, v18, v19
	v_cvt_pk_bf16_f32 v199, v20, v21
	global_store_dwordx4 v155, v[196:199], s[26:27] offset:16
	v_mul_f32_e32 v200, v187, v186
	v_add_u32_e32 v155, 0x2c0000, v201
	v_fma_f32 v188, -v200, v212, v213
	v_fma_f32 v189, -v200, v214, v215
	v_fma_f32 v190, -v200, v216, v217
	v_fma_f32 v191, -v200, v218, v219
	v_fma_f32 v192, -v200, v220, v221
	v_fma_f32 v193, -v200, v222, v223
	v_fma_f32 v194, -v200, v224, v225
	v_fma_f32 v195, -v200, v226, v227
	v_fma_f32 v14, v187, v14, v188
	v_fma_f32 v15, v187, v15, v189
	v_fma_f32 v16, v187, v16, v190
	v_fma_f32 v17, v187, v17, v191
	v_fma_f32 v10, v187, v10, v192
	v_fma_f32 v11, v187, v11, v193
	v_fma_f32 v12, v187, v12, v194
	v_fma_f32 v13, v187, v13, v195
	v_max_f32_e32 v14, 0, v14
	v_max_f32_e32 v15, 0, v15
	v_max_f32_e32 v16, 0, v16
	v_max_f32_e32 v17, 0, v17
	v_max_f32_e32 v10, 0, v10
	v_max_f32_e32 v11, 0, v11
	v_max_f32_e32 v12, 0, v12
	v_max_f32_e32 v13, 0, v13
	v_mul_f32_e32 v14, v14, v14
	v_mul_f32_e32 v15, v15, v15
	v_mul_f32_e32 v16, v16, v16
	v_mul_f32_e32 v17, v17, v17
	v_mul_f32_e32 v10, v10, v10
	v_mul_f32_e32 v11, v11, v11
	v_mul_f32_e32 v12, v12, v12
	v_mul_f32_e32 v13, v13, v13
	v_cvt_pk_bf16_f32 v196, v14, v15
	v_cvt_pk_bf16_f32 v197, v16, v17
	v_cvt_pk_bf16_f32 v198, v10, v11
	v_cvt_pk_bf16_f32 v199, v12, v13
	global_store_dwordx4 v155, v[196:199], s[26:27]
	v_fma_f32 v188, -v200, v228, v229
	v_fma_f32 v189, -v200, v230, v231
	v_fma_f32 v190, -v200, v232, v233
	v_fma_f32 v191, -v200, v234, v235
	v_fma_f32 v192, -v200, v236, v237
	v_fma_f32 v193, -v200, v238, v239
	v_fma_f32 v194, -v200, v240, v241
	v_fma_f32 v195, -v200, v242, v243
	v_fma_f32 v6, v187, v6, v188
	v_fma_f32 v7, v187, v7, v189
	v_fma_f32 v8, v187, v8, v190
	v_fma_f32 v9, v187, v9, v191
	v_fma_f32 v2, v187, v2, v192
	v_fma_f32 v3, v187, v3, v193
	v_fma_f32 v4, v187, v4, v194
	v_fma_f32 v5, v187, v5, v195
	v_max_f32_e32 v6, 0, v6
	v_max_f32_e32 v7, 0, v7
	v_max_f32_e32 v8, 0, v8
	v_max_f32_e32 v9, 0, v9
	v_max_f32_e32 v2, 0, v2
	v_max_f32_e32 v3, 0, v3
	v_max_f32_e32 v4, 0, v4
	v_max_f32_e32 v5, 0, v5
	v_mul_f32_e32 v6, v6, v6
	v_mul_f32_e32 v7, v7, v7
	v_mul_f32_e32 v8, v8, v8
	v_mul_f32_e32 v9, v9, v9
	v_mul_f32_e32 v2, v2, v2
	v_mul_f32_e32 v3, v3, v3
	v_mul_f32_e32 v4, v4, v4
	v_mul_f32_e32 v5, v5, v5
	v_cvt_pk_bf16_f32 v196, v6, v7
	v_cvt_pk_bf16_f32 v197, v8, v9
	v_cvt_pk_bf16_f32 v198, v2, v3
	v_cvt_pk_bf16_f32 v199, v4, v5
	global_store_dwordx4 v155, v[196:199], s[26:27] offset:16
	s_andn2_b64 vcc, exec, s[22:23]
	s_mov_b64 s[22:23], -1
	s_cbranch_vccnz .LBB0_164
	s_nop 0
	v_lshl_add_u32 v2, s16, 8, v144
	v_ashrrev_i32_e32 v3, 31, v2
	v_lshlrev_b64 v[2:3], 8, v[2:3]
	v_lshl_add_u64 v[6:7], v[136:137], 0, v[2:3]
	global_load_dwordx4 v[2:5], v[6:7], off
	global_load_dwordx4 v[222:225], v[6:7], off offset:16
	global_load_dwordx4 v[226:229], v[6:7], off offset:32
	global_load_dwordx4 v[230:233], v[6:7], off offset:48
	global_load_dwordx4 v[234:237], v[6:7], off offset:64
	global_load_dwordx4 v[238:241], v[6:7], off offset:80
	global_load_dwordx4 v[242:245], v[6:7], off offset:96
	global_load_dwordx4 v[246:249], v[6:7], off offset:112
	v_lshl_or_b32 v18, s14, 8, v146
	v_lshlrev_b32_e32 v18, 2, v18
	v_add_u32_e32 v22, 0x8000, v18
	v_add_u32_e32 v24, 0x10000, v18
	v_add_u32_e32 v26, 0x18000, v18
	v_add_u32_e32 v21, 0x20000, v18
	v_add_u32_e32 v23, 0x28000, v18
	v_add_u32_e32 v25, 0x30000, v18
	v_add_u32_e32 v27, 0x38000, v18
	global_load_dword v20, v18, s[4:5]
	global_load_dword v22, v22, s[4:5]
	global_load_dword v24, v24, s[4:5]
	global_load_dword v26, v26, s[4:5]
	global_load_dword v21, v21, s[4:5]
	global_load_dword v23, v23, s[4:5]
	global_load_dword v25, v25, s[4:5]
	global_load_dword v27, v27, s[4:5]
	s_and_b32 s15, s39, 1
	s_waitcnt vmcnt(0) lgkmcnt(0)
	v_add_f32_e32 v2, v2, v4
	v_add_f32_e32 v8, 0, v2
	v_add_f32_e32 v2, v3, v5
	v_add_f32_e32 v9, 0, v2
	v_add_f32_e32 v2, v222, v224
	v_add_f32_e32 v8, v8, v2
	v_add_f32_e32 v2, v223, v225
	v_add_f32_e32 v9, v9, v2
	v_add_f32_e32 v2, v226, v228
	v_add_f32_e32 v8, v8, v2
	v_add_f32_e32 v2, v227, v229
	v_add_f32_e32 v9, v9, v2
	v_add_f32_e32 v2, v230, v232
	v_add_f32_e32 v8, v8, v2
	v_add_f32_e32 v2, v231, v233
	v_add_f32_e32 v9, v9, v2
	v_add_f32_e32 v2, v234, v236
	v_add_f32_e32 v8, v8, v2
	v_add_f32_e32 v2, v235, v237
	v_add_f32_e32 v9, v9, v2
	v_add_f32_e32 v2, v238, v240
	v_add_f32_e32 v8, v8, v2
	v_add_f32_e32 v2, v239, v241
	v_add_f32_e32 v9, v9, v2
	v_add_f32_e32 v2, v242, v244
	v_add_f32_e32 v8, v8, v2
	v_add_f32_e32 v2, v243, v245
	v_add_f32_e32 v9, v9, v2
	v_add_f32_e32 v2, v246, v248
	v_add_f32_e32 v3, v247, v249
	v_add_f32_e32 v2, v8, v2
	v_add_f32_e32 v3, v9, v3
	ds_bpermute_b32 v4, v145, v2
	ds_bpermute_b32 v5, v145, v3
	s_and_saveexec_b64 s[22:23], s[0:1]
	s_cbranch_execz .LBB0_179
	s_waitcnt lgkmcnt(1)
	v_add_f32_e32 v2, v2, v4
	v_mul_f32_e32 v2, 0x3a000000, v2
	s_waitcnt lgkmcnt(0)
	v_add_f32_e32 v3, v3, v5
	v_mul_f32_e32 v4, v2, v2
	v_fma_f32 v3, v3, s61, -v4
	v_add_f32_e32 v3, 0x3727c5ac, v3
	v_rsq_f32_e32 v3, v3
	v_lshl_add_u32 v4, s15, 11, v151
	ds_write_b64 v4, v[2:3]
.LBB0_179:
	s_or_b64 exec, exec, s[22:23]
	s_waitcnt lgkmcnt(0)
	v_lshl_add_u32 v12, s15, 12, v147
	s_andn2_b64 vcc, exec, s[6:7]
	v_pk_add_f32 v[2:3], v[20:21], v[22:23]
	v_pk_add_f32 v[4:5], v[24:25], v[26:27]
	s_nop 0
	v_pk_add_f32 v[2:3], v[2:3], v[4:5]
	ds_write_b64 v12, v[2:3]
	s_cbranch_vccnz .LBB0_163
	s_barrier
	s_branch .LBB0_163

; #define LAS __attribute__((address_space(3)))
; __device__ __forceinline__ float shflx(float v, int k, int lane) { return __int_as_float(__builtin_amdgcn_ds_bpermute((lane ^ k) << 2, __float_as_int(v))); }
;     __device__ __forceinline__ void prepare(const pg8::Unit& u, LAS unsigned char* lds, int par, int tid) const { F.prepare(u, lds, par, tid); }
;     __device__ __forceinline__ void prepare(const pg8::Unit& u, LAS unsigned char* lds, int par, int tid) const { F.prepare(u, lds, par, tid); }
;     __device__ __forceinline__ void prepare(const pg8::Unit& u, LAS unsigned char* lds, int par, int tid) const { F.prepare(u, lds, par, tid); }
;     __device__ __forceinline__ void prepare(const pg8::Unit& u, LAS unsigned char* lds, int par, int tid) const {
;         if (stats == nullptr) return;
;         const int h = tid >> 8, tt = tid & 255, rl = tt >> 1, part = tt & 1, lrow = (rl >> 6) * 128 + h * 64 + (rl & 63);
;         const float* sp = stats + ((size_t)(u.pm * 256 + lrow) * 32 + part * 16) * 2;
;         float s1 = 0.f, s2 = 0.f;
; #pragma unroll
;         for (int i = 0; i < 8; ++i) { const f32x4 v = *(const f32x4*)(sp + 4 * i); s1 += v[0] + v[2]; s2 += v[1] + v[3]; }
;         s1 += shflx(s1, 1, tid & 63); s2 += shflx(s2, 1, tid & 63);
;         const float mu = s1 * (1.f / D), var = s2 * (1.f / D) - mu * mu, rstd = __builtin_amdgcn_rsqf(var + LN_EPS);
;         if (part == 0) { LAS float* rs = (LAS float*)(lds + RS_OFF) + (par * 256 + lrow) * 2; rs[0] = mu; rs[1] = rstd; }
;         if (cs != nullptr) {
;             const int col = u.pn * 256 + tt;
;             const float c = (cs[col] + cs[N + col]) + (cs[2 * N + col] + cs[3 * N + col]);
;             const float b = (cs[4 * N + col] + cs[5 * N + col]) + (cs[6 * N + col] + cs[7 * N + col]);
;             LAS float* cv = (LAS float*)(lds + CV_OFF) + ((par * 2 + h) * 256 + tt) * 2; cv[0] = c; cv[1] = b;
;         }
.LBB0_825:
	s_andn2_b64 vcc, exec, s[24:25]
	s_mov_b64 s[24:25], -1
	s_cbranch_vccnz .LBB0_541
	s_and_b64 vcc, exec, s[44:45]
	s_cbranch_vccnz .LBB0_830
	v_lshl_add_u32 v2, s18, 8, v179
	v_ashrrev_i32_e32 v3, 31, v2
	v_lshlrev_b64 v[2:3], 8, v[2:3]
	v_lshl_add_u64 v[6:7], v[142:143], 0, v[2:3]
	s_waitcnt lgkmcnt(0)
	global_load_dwordx4 v[2:5], v[6:7], off
	global_load_dwordx4 v[222:225], v[6:7], off offset:16
	global_load_dwordx4 v[226:229], v[6:7], off offset:32
	global_load_dwordx4 v[230:233], v[6:7], off offset:48
	global_load_dwordx4 v[234:237], v[6:7], off offset:64
	global_load_dwordx4 v[238:241], v[6:7], off offset:80
	global_load_dwordx4 v[242:245], v[6:7], off offset:96
	global_load_dwordx4 v[246:249], v[6:7], off offset:112
	v_lshl_or_b32 v18, s16, 8, v180
	v_lshlrev_b32_e32 v18, 2, v18
	v_add_u32_e32 v22, 0x7800, v18
	v_add_u32_e32 v24, 0xf000, v18
	v_add_u32_e32 v26, 0x16800, v18
	v_add_u32_e32 v21, 0x1e000, v18
	v_add_u32_e32 v23, 0x25800, v18
	v_add_u32_e32 v25, 0x2d000, v18
	v_add_u32_e32 v27, 0x34800, v18
	global_load_dword v20, v18, s[4:5]
	global_load_dword v22, v22, s[4:5]
	global_load_dword v24, v24, s[4:5]
	global_load_dword v26, v26, s[4:5]
	global_load_dword v21, v21, s[4:5]
	global_load_dword v23, v23, s[4:5]
	global_load_dword v25, v25, s[4:5]
	global_load_dword v27, v27, s[4:5]
	s_and_b32 s2, s66, 1
	s_waitcnt vmcnt(0) lgkmcnt(0)
	v_add_f32_e32 v0, v2, v4
	v_add_f32_e32 v2, v3, v5
	v_add_f32_e32 v8, 0, v2
	v_add_f32_e32 v0, 0, v0
	v_add_f32_e32 v2, v222, v224
	v_add_f32_e32 v0, v0, v2
	v_add_f32_e32 v2, v223, v225
	v_add_f32_e32 v8, v8, v2
	v_add_f32_e32 v2, v226, v228
	v_add_f32_e32 v0, v0, v2
	v_add_f32_e32 v2, v227, v229
	v_add_f32_e32 v8, v8, v2
	v_add_f32_e32 v2, v230, v232
	v_add_f32_e32 v0, v0, v2
	v_add_f32_e32 v2, v231, v233
	v_add_f32_e32 v8, v8, v2
	v_add_f32_e32 v2, v234, v236
	v_add_f32_e32 v0, v0, v2
	v_add_f32_e32 v2, v235, v237
	v_add_f32_e32 v8, v8, v2
	v_add_f32_e32 v2, v238, v240
	v_add_f32_e32 v0, v0, v2
	v_add_f32_e32 v2, v239, v241
	v_add_f32_e32 v8, v8, v2
	v_add_f32_e32 v2, v242, v244
	v_add_f32_e32 v0, v0, v2
	v_add_f32_e32 v2, v243, v245
	v_add_f32_e32 v8, v8, v2
	v_add_f32_e32 v2, v246, v248
	v_add_f32_e32 v0, v0, v2
	v_add_f32_e32 v2, v247, v249
	v_add_f32_e32 v2, v8, v2
	ds_bpermute_b32 v3, v181, v0
	ds_bpermute_b32 v4, v181, v2
	s_and_saveexec_b64 s[24:25], s[42:43]
	s_cbranch_execz .LBB0_829
	s_waitcnt lgkmcnt(1)
	v_add_f32_e32 v0, v0, v3
	s_waitcnt lgkmcnt(0)
	v_add_f32_e32 v4, v2, v4
	v_mul_f32_e32 v2, 0x3a000000, v0
	v_mul_f32_e32 v0, v2, v2
	s_mov_b32 s17, 0x3a000000
	v_fma_f32 v0, v4, s17, -v0
	v_add_f32_e32 v0, 0x3727c5ac, v0
	v_rsq_f32_e32 v3, v0
	v_lshl_add_u32 v0, s2, 11, v182
	ds_write_b64 v0, v[2:3]
.LBB0_829:
	s_or_b64 exec, exec, s[24:25]
	s_waitcnt lgkmcnt(0)
	v_lshl_add_u32 v0, s2, 12, v183
	v_pk_add_f32 v[2:3], v[20:21], v[22:23]
	v_pk_add_f32 v[4:5], v[24:25], v[26:27]
	s_nop 0
	v_pk_add_f32 v[2:3], v[2:3], v[4:5]
	ds_write_b64 v0, v[2:3]
